# last gMLP unit: one wave per workgroup touches an eighth of the K|V block the workgroup's first memory-attention unit loads next (8 workgroups per XCD cover the block), so those loads hit L2
# speedup vs baseline: 1.0089x; 1.0089x over previous
.Lgm_ng2:
	s_mov_b64 exec, s[28:29]
	s_waitcnt lgkmcnt(0)
	s_barrier
	s_add_u32 s70, s16, s92
	s_min_u32 s71, s70, 0x5ff
	s_mul_hi_u32 s18, s71, 0xaaaaaaab
	s_lshr_b32 s18, s18, 2
	s_mul_i32 s17, s18, 6
	s_sub_u32 s17, s71, s17
	s_mul_i32 s28, s18, 0x3000
	s_add_u32 s4, s6, s28
	s_addc_u32 s5, s7, 0
	s_add_u32 s4, s4, 0x3600000
	s_addc_u32 s5, s5, 0
	global_load_dwordx4 v[98:101], v1, s[4:5]
	global_load_dwordx4 v[102:105], v1, s[4:5] offset:16
	global_load_dwordx4 v[106:109], v1, s[4:5] offset:32
	s_mul_i32 s28, s18, 0x30000
	s_lshl_b32 s29, s17, 8
	s_add_u32 s28, s28, s29
	s_add_u32 s8, s6, s28
	s_addc_u32 s9, s7, 0
	s_add_u32 s14, s8, 0xd200000
	s_addc_u32 s15, s9, 0
	s_add_u32 s8, s8, 0x10200000
	s_addc_u32 s9, s9, 0
	global_load_dwordx4 v[110:113], v85, s[8:9]
	global_load_dwordx4 v[114:117], v85, s[8:9] offset:16
	global_load_dwordx4 v[118:121], v85, s[8:9] offset:32
	global_load_dwordx4 v[122:125], v85, s[8:9] offset:48
	s_lshl_b32 s28, s17, 15
	s_add_u32 s10, s6, s28
	s_addc_u32 s11, s7, 0
	s_add_u32 s10, s10, 0x3200000
	s_addc_u32 s11, s11, 0
	global_load_dwordx4 v[126:129], v90, s[10:11]
	global_load_dwordx4 v[130:133], v90, s[10:11] offset:64
	global_load_dwordx4 v[134:137], v90, s[10:11] offset:128
	global_load_dwordx4 v[138:141], v90, s[10:11] offset:192
	s_lshl_b32 s28, s17, 9
	s_add_u32 s12, s78, s28
	s_addc_u32 s13, s79, 0
	global_load_dword v188, v91, s[12:13]
	global_load_dwordx4 v[172:175], v92, s[14:15]
	global_load_dwordx4 v[176:179], v92, s[14:15] offset:64
	global_load_dwordx4 v[180:183], v92, s[14:15] offset:128
	global_load_dwordx4 v[184:187], v92, s[14:15] offset:192
	s_cmpk_lt_u32 s70, 0x600
	s_cbranch_scc1 .Lgm_kvt_p
	v_readfirstlane_b32 s28, v83
	s_nop 3
	s_cmp_gt_u32 s28, 63
	s_cbranch_scc1 .Lgm_kvt_p
	s_lshr_b32 s28, s2, 6
	s_lshl_b32 s28, s28, 19
	s_bfe_u32 s29, s2, 0x30003
	s_lshl_b32 s29, s29, 16
	s_add_u32 s28, s28, s29
	s_and_b32 s29, s2, 3
	s_lshl_b32 s29, s29, 7
	s_add_u32 s28, s28, s29
	s_add_u32 s28, s28, 0x3e00400
	s_add_u32 s100, s6, s28
	s_addc_u32 s101, s7, 0
	v_lshrrev_b32_e32 v249, 1, v197
	v_lshlrev_b32_e32 v249, 11, v249
	v_and_b32_e32 v248, 1, v197
	v_lshl_add_u32 v249, v248, 9, v249
	s_nop 0
	global_load_dword v248, v249, s[100:101]
.Lgm_kvt_p:
	s_mul_hi_u32 s18, s16, 0xaaaaaaab
	s_lshr_b32 s18, s18, 2
	s_mul_i32 s17, s18, 6
	s_sub_u32 s17, s16, s17
	s_lshl_b32 s28, s17, 9
	v_add_u32_e32 v89, s28, v88
	s_mul_i32 s28, s18, 0x40000
	s_lshl_b32 s29, s17, 8
	s_add_u32 s28, s28, s29
	s_add_u32 s68, s0, s28
	s_addc_u32 s69, s1, 0
	s_waitcnt vmcnt(25)
	ds_read_b128 v[200:203], v89
	ds_read_b128 v[204:207], v89 offset:16
	ds_read_b128 v[208:211], v89 offset:3072
	ds_read_b128 v[212:215], v89 offset:3088
	v_add_f32_e32 v77, v4, v6
	v_add_f32_e32 v154, v5, v7
	v_add_f32_e32 v155, v8, v10
	v_add_f32_e32 v189, v9, v11
	v_add_f32_e32 v77, v77, v155
	v_add_f32_e32 v154, v154, v189
	v_add_f32_e32 v155, v12, v14
	v_add_f32_e32 v189, v13, v15
	v_add_f32_e32 v77, v77, v155
	v_add_f32_e32 v154, v154, v189
	s_nop 1
	v_add_f32_dpp v77, v77, v77 quad_perm:[1,0,3,2] row_mask:0xf bank_mask:0xf
	v_add_f32_dpp v154, v154, v154 quad_perm:[1,0,3,2] row_mask:0xf bank_mask:0xf
	v_mul_f32_e32 v155, 0x3aaaaaab, v77
	v_mul_f32_e32 v155, v155, v155
	s_mov_b32 s28, 0x3aaaaaab
	v_fma_f32 v154, v154, s28, -v155
	v_add_f32_e32 v154, 0x358637bd, v154
	v_rsq_f32_e32 v154, v154
	ds_read_b128 v[216:219], v89 offset:32
	ds_read_b128 v[220:223], v89 offset:48
	ds_read_b128 v[224:227], v89 offset:3104
	ds_read_b128 v[228:231], v89 offset:3120
	s_waitcnt lgkmcnt(4)
	v_lshlrev_b32_e32 v155, 16, v16
	v_and_b32_e32 v189, 0xffff0000, v16
	v_fmac_f32_e32 v155, 0xbaaaaaab, v77
	v_fmac_f32_e32 v189, 0xbaaaaaab, v77
	v_mul_f32_e32 v155, v155, v154
	v_mul_f32_e32 v189, v189, v154
	v_fma_f32 v155, v200, v155, v208
	v_fma_f32 v189, v201, v189, v209
	v_cvt_pk_bf16_f32 v16, v155, v189
	ds_write_b16 v86, v16
	ds_write_b16_d16_hi v86, v16 offset:272
	v_lshlrev_b32_e32 v155, 16, v17
	v_and_b32_e32 v189, 0xffff0000, v17
	v_fmac_f32_e32 v155, 0xbaaaaaab, v77
	v_fmac_f32_e32 v189, 0xbaaaaaab, v77
	v_mul_f32_e32 v155, v155, v154
	v_mul_f32_e32 v189, v189, v154
	v_fma_f32 v155, v202, v155, v210
	v_fma_f32 v189, v203, v189, v211
	v_cvt_pk_bf16_f32 v17, v155, v189
	ds_write_b16 v86, v17 offset:544
	ds_write_b16_d16_hi v86, v17 offset:816
	v_lshlrev_b32_e32 v155, 16, v18
	v_and_b32_e32 v189, 0xffff0000, v18
	v_fmac_f32_e32 v155, 0xbaaaaaab, v77
	v_fmac_f32_e32 v189, 0xbaaaaaab, v77
	v_mul_f32_e32 v155, v155, v154
	v_mul_f32_e32 v189, v189, v154
	v_fma_f32 v155, v204, v155, v212
	v_fma_f32 v189, v205, v189, v213
	v_cvt_pk_bf16_f32 v18, v155, v189
	ds_write_b16 v86, v18 offset:1088
	ds_write_b16_d16_hi v86, v18 offset:1360
	v_lshlrev_b32_e32 v155, 16, v19
	v_and_b32_e32 v189, 0xffff0000, v19
	v_fmac_f32_e32 v155, 0xbaaaaaab, v77
	v_fmac_f32_e32 v189, 0xbaaaaaab, v77
	v_mul_f32_e32 v155, v155, v154
	v_mul_f32_e32 v189, v189, v154
	v_fma_f32 v155, v206, v155, v214
	v_fma_f32 v189, v207, v189, v215
	v_cvt_pk_bf16_f32 v19, v155, v189
	ds_write_b16 v86, v19 offset:1632
	ds_write_b16_d16_hi v86, v19 offset:1904
	ds_read_b128 v[200:203], v89 offset:64
	ds_read_b128 v[204:207], v89 offset:80
	ds_read_b128 v[208:211], v89 offset:3136
	ds_read_b128 v[212:215], v89 offset:3152
	s_waitcnt lgkmcnt(4)
	v_lshlrev_b32_e32 v155, 16, v20
	v_and_b32_e32 v189, 0xffff0000, v20
	v_fmac_f32_e32 v155, 0xbaaaaaab, v77
	v_fmac_f32_e32 v189, 0xbaaaaaab, v77
	v_mul_f32_e32 v155, v155, v154
	v_mul_f32_e32 v189, v189, v154
	v_fma_f32 v155, v216, v155, v224
	v_fma_f32 v189, v217, v189, v225
	v_cvt_pk_bf16_f32 v20, v155, v189
	ds_write_b16 v86, v20 offset:2176
	ds_write_b16_d16_hi v86, v20 offset:2448
	v_lshlrev_b32_e32 v155, 16, v21
	v_and_b32_e32 v189, 0xffff0000, v21
	v_fmac_f32_e32 v155, 0xbaaaaaab, v77
	v_fmac_f32_e32 v189, 0xbaaaaaab, v77
	v_mul_f32_e32 v155, v155, v154
	v_mul_f32_e32 v189, v189, v154
	v_fma_f32 v155, v218, v155, v226
	v_fma_f32 v189, v219, v189, v227
	v_cvt_pk_bf16_f32 v21, v155, v189
	ds_write_b16 v86, v21 offset:2720
	ds_write_b16_d16_hi v86, v21 offset:2992
	v_lshlrev_b32_e32 v155, 16, v22
	v_and_b32_e32 v189, 0xffff0000, v22
	v_fmac_f32_e32 v155, 0xbaaaaaab, v77
	v_fmac_f32_e32 v189, 0xbaaaaaab, v77
	v_mul_f32_e32 v155, v155, v154
	v_mul_f32_e32 v189, v189, v154
	v_fma_f32 v155, v220, v155, v228
	v_fma_f32 v189, v221, v189, v229
	v_cvt_pk_bf16_f32 v22, v155, v189
	ds_write_b16 v86, v22 offset:3264
	ds_write_b16_d16_hi v86, v22 offset:3536
	v_lshlrev_b32_e32 v155, 16, v23
	v_and_b32_e32 v189, 0xffff0000, v23
	v_fmac_f32_e32 v155, 0xbaaaaaab, v77
	v_fmac_f32_e32 v189, 0xbaaaaaab, v77
	v_mul_f32_e32 v155, v155, v154
	v_mul_f32_e32 v189, v189, v154
	v_fma_f32 v155, v222, v155, v230
	v_fma_f32 v189, v223, v189, v231
	v_cvt_pk_bf16_f32 v23, v155, v189
	ds_write_b16 v86, v23 offset:3808
	ds_write_b16_d16_hi v86, v23 offset:4080
	ds_read_b128 v[216:219], v89 offset:96
	ds_read_b128 v[220:223], v89 offset:112
	ds_read_b128 v[224:227], v89 offset:3168
	ds_read_b128 v[228:231], v89 offset:3184
	s_waitcnt lgkmcnt(4)
	v_lshlrev_b32_e32 v155, 16, v24
	v_and_b32_e32 v189, 0xffff0000, v24
	v_fmac_f32_e32 v155, 0xbaaaaaab, v77
	v_fmac_f32_e32 v189, 0xbaaaaaab, v77
	v_mul_f32_e32 v155, v155, v154
	v_mul_f32_e32 v189, v189, v154
	v_fma_f32 v155, v200, v155, v208
	v_fma_f32 v189, v201, v189, v209
	v_cvt_pk_bf16_f32 v24, v155, v189
	ds_write_b16 v86, v24 offset:4352
	ds_write_b16_d16_hi v86, v24 offset:4624
	v_lshlrev_b32_e32 v155, 16, v25
	v_and_b32_e32 v189, 0xffff0000, v25
	v_fmac_f32_e32 v155, 0xbaaaaaab, v77
	v_fmac_f32_e32 v189, 0xbaaaaaab, v77
	v_mul_f32_e32 v155, v155, v154
	v_mul_f32_e32 v189, v189, v154
	v_fma_f32 v155, v202, v155, v210
	v_fma_f32 v189, v203, v189, v211
	v_cvt_pk_bf16_f32 v25, v155, v189
	ds_write_b16 v86, v25 offset:4896
	ds_write_b16_d16_hi v86, v25 offset:5168
	v_lshlrev_b32_e32 v155, 16, v26
	v_and_b32_e32 v189, 0xffff0000, v26
	v_fmac_f32_e32 v155, 0xbaaaaaab, v77
	v_fmac_f32_e32 v189, 0xbaaaaaab, v77
	v_mul_f32_e32 v155, v155, v154
	v_mul_f32_e32 v189, v189, v154
	v_fma_f32 v155, v204, v155, v212
	v_fma_f32 v189, v205, v189, v213
	v_cvt_pk_bf16_f32 v26, v155, v189
	ds_write_b16 v86, v26 offset:5440
	ds_write_b16_d16_hi v86, v26 offset:5712
	v_lshlrev_b32_e32 v155, 16, v27
	v_and_b32_e32 v189, 0xffff0000, v27
	v_fmac_f32_e32 v155, 0xbaaaaaab, v77
	v_fmac_f32_e32 v189, 0xbaaaaaab, v77
	v_mul_f32_e32 v155, v155, v154
	v_mul_f32_e32 v189, v189, v154
	v_fma_f32 v155, v206, v155, v214
	v_fma_f32 v189, v207, v189, v215
	v_cvt_pk_bf16_f32 v27, v155, v189
	ds_write_b16 v86, v27 offset:5984
	ds_write_b16_d16_hi v86, v27 offset:6256
	s_waitcnt lgkmcnt(0)
	v_lshlrev_b32_e32 v155, 16, v28
	v_and_b32_e32 v189, 0xffff0000, v28
	v_fmac_f32_e32 v155, 0xbaaaaaab, v77
	v_fmac_f32_e32 v189, 0xbaaaaaab, v77
	v_mul_f32_e32 v155, v155, v154
	v_mul_f32_e32 v189, v189, v154
	v_fma_f32 v155, v216, v155, v224
	v_fma_f32 v189, v217, v189, v225
	v_cvt_pk_bf16_f32 v28, v155, v189
	ds_write_b16 v86, v28 offset:6528
	ds_write_b16_d16_hi v86, v28 offset:6800
	v_lshlrev_b32_e32 v155, 16, v29
	v_and_b32_e32 v189, 0xffff0000, v29
	v_fmac_f32_e32 v155, 0xbaaaaaab, v77
	v_fmac_f32_e32 v189, 0xbaaaaaab, v77
	v_mul_f32_e32 v155, v155, v154
	v_mul_f32_e32 v189, v189, v154
	v_fma_f32 v155, v218, v155, v226
	v_fma_f32 v189, v219, v189, v227
	v_cvt_pk_bf16_f32 v29, v155, v189
	ds_write_b16 v86, v29 offset:7072
	ds_write_b16_d16_hi v86, v29 offset:7344
	v_lshlrev_b32_e32 v155, 16, v30
	v_and_b32_e32 v189, 0xffff0000, v30
	v_fmac_f32_e32 v155, 0xbaaaaaab, v77
	v_fmac_f32_e32 v189, 0xbaaaaaab, v77
	v_mul_f32_e32 v155, v155, v154
	v_mul_f32_e32 v189, v189, v154
	v_fma_f32 v155, v220, v155, v228
	v_fma_f32 v189, v221, v189, v229
	v_cvt_pk_bf16_f32 v30, v155, v189
	ds_write_b16 v86, v30 offset:7616
	ds_write_b16_d16_hi v86, v30 offset:7888
	v_lshlrev_b32_e32 v155, 16, v31
	v_and_b32_e32 v189, 0xffff0000, v31
	v_fmac_f32_e32 v155, 0xbaaaaaab, v77
	v_fmac_f32_e32 v189, 0xbaaaaaab, v77
	v_mul_f32_e32 v155, v155, v154
	v_mul_f32_e32 v189, v189, v154
	v_fma_f32 v155, v222, v155, v230
	v_fma_f32 v189, v223, v189, v231
	v_cvt_pk_bf16_f32 v31, v155, v189
	ds_write_b16 v86, v31 offset:8160
	ds_write_b16_d16_hi v86, v31 offset:8432
	s_waitcnt lgkmcnt(0)
	s_barrier
	s_waitcnt vmcnt(16)
	ds_read_b128 v[200:203], v87 offset:0
	ds_read_b128 v[204:207], v87 offset:64
	ds_read_b128 v[208:211], v87 offset:128
	ds_read_b128 v[212:215], v87 offset:192
	ds_read_b128 v[216:219], v87 offset:1088
	ds_read_b128 v[220:223], v87 offset:1152
	ds_read_b128 v[224:227], v87 offset:1216
	ds_read_b128 v[228:231], v87 offset:1280
	s_waitcnt lgkmcnt(4)
	v_mfma_f32_16x16x32_bf16 v[78:81], v[200:203], v[32:35], 0
	v_mfma_f32_16x16x32_bf16 v[78:81], v[204:207], v[36:39], v[78:81]
	v_mfma_f32_16x16x32_bf16 v[78:81], v[208:211], v[40:43], v[78:81]
	v_mfma_f32_16x16x32_bf16 v[78:81], v[212:215], v[44:47], v[78:81]
	ds_read_b128 v[200:203], v87 offset:8704
	ds_read_b128 v[204:207], v87 offset:8768
	ds_read_b128 v[208:211], v87 offset:8832
	ds_read_b128 v[212:215], v87 offset:8896
	s_waitcnt lgkmcnt(4)
	v_mfma_f32_16x16x32_bf16 v[94:97], v[216:219], v[32:35], 0
	v_mfma_f32_16x16x32_bf16 v[94:97], v[220:223], v[36:39], v[94:97]
	v_mfma_f32_16x16x32_bf16 v[94:97], v[224:227], v[40:43], v[94:97]
	v_mfma_f32_16x16x32_bf16 v[94:97], v[228:231], v[44:47], v[94:97]
	ds_read_b128 v[216:219], v87 offset:9792
	ds_read_b128 v[220:223], v87 offset:9856
	ds_read_b128 v[224:227], v87 offset:9920
	ds_read_b128 v[228:231], v87 offset:9984
	s_waitcnt lgkmcnt(4)
	v_mfma_f32_16x16x32_bf16 v[142:145], v[200:203], v[32:35], 0
	v_mfma_f32_16x16x32_bf16 v[142:145], v[204:207], v[36:39], v[142:145]
	v_mfma_f32_16x16x32_bf16 v[142:145], v[208:211], v[40:43], v[142:145]
	v_mfma_f32_16x16x32_bf16 v[142:145], v[212:215], v[44:47], v[142:145]
	ds_read_b128 v[200:203], v87 offset:17408
	ds_read_b128 v[204:207], v87 offset:17472
	ds_read_b128 v[208:211], v87 offset:17536
	ds_read_b128 v[212:215], v87 offset:17600
	v_add_f32_e32 v78, v64, v78
	v_add_f32_e32 v79, v64, v79
	v_add_f32_e32 v80, v64, v80
	v_add_f32_e32 v81, v64, v81
	v_lshlrev_b32_e32 v155, 16, v48
	v_and_b32_e32 v189, 0xffff0000, v48
	v_mul_f32_e32 v78, v78, v155
	v_mul_f32_e32 v79, v79, v189
	v_lshlrev_b32_e32 v155, 16, v49
	v_and_b32_e32 v189, 0xffff0000, v49
	v_mul_f32_e32 v80, v80, v155
	v_mul_f32_e32 v81, v81, v189
	v_cvt_pk_bf16_f32 v48, v78, v79
	v_cvt_pk_bf16_f32 v49, v80, v81
	v_add_f32_e32 v94, v64, v94
	v_add_f32_e32 v95, v64, v95
	v_add_f32_e32 v96, v64, v96
	v_add_f32_e32 v97, v64, v97
	v_lshlrev_b32_e32 v155, 16, v50
	v_and_b32_e32 v189, 0xffff0000, v50
	v_mul_f32_e32 v94, v94, v155
	v_mul_f32_e32 v95, v95, v189
	v_lshlrev_b32_e32 v155, 16, v51
	v_and_b32_e32 v189, 0xffff0000, v51
	v_mul_f32_e32 v96, v96, v155
	v_mul_f32_e32 v97, v97, v189
	v_cvt_pk_bf16_f32 v50, v94, v95
	v_cvt_pk_bf16_f32 v51, v96, v97
	global_store_dwordx4 v93, v[48:51], s[68:69]
	s_waitcnt lgkmcnt(4)
	v_mfma_f32_16x16x32_bf16 v[146:149], v[216:219], v[32:35], 0
	v_mfma_f32_16x16x32_bf16 v[146:149], v[220:223], v[36:39], v[146:149]
	v_mfma_f32_16x16x32_bf16 v[146:149], v[224:227], v[40:43], v[146:149]
	v_mfma_f32_16x16x32_bf16 v[146:149], v[228:231], v[44:47], v[146:149]
	ds_read_b128 v[216:219], v87 offset:18496
	ds_read_b128 v[220:223], v87 offset:18560
	ds_read_b128 v[224:227], v87 offset:18624
	ds_read_b128 v[228:231], v87 offset:18688
	s_waitcnt lgkmcnt(4)
	v_mfma_f32_16x16x32_bf16 v[78:81], v[200:203], v[32:35], 0
	v_mfma_f32_16x16x32_bf16 v[78:81], v[204:207], v[36:39], v[78:81]
	v_mfma_f32_16x16x32_bf16 v[78:81], v[208:211], v[40:43], v[78:81]
	v_mfma_f32_16x16x32_bf16 v[78:81], v[212:215], v[44:47], v[78:81]
	ds_read_b128 v[200:203], v87 offset:26112
	ds_read_b128 v[204:207], v87 offset:26176
	ds_read_b128 v[208:211], v87 offset:26240
	ds_read_b128 v[212:215], v87 offset:26304
	v_add_f32_e32 v142, v64, v142
	v_add_f32_e32 v143, v64, v143
	v_add_f32_e32 v144, v64, v144
	v_add_f32_e32 v145, v64, v145
	v_lshlrev_b32_e32 v155, 16, v52
	v_and_b32_e32 v189, 0xffff0000, v52
	v_mul_f32_e32 v142, v142, v155
	v_mul_f32_e32 v143, v143, v189
	v_lshlrev_b32_e32 v155, 16, v53
	v_and_b32_e32 v189, 0xffff0000, v53
	v_mul_f32_e32 v144, v144, v155
	v_mul_f32_e32 v145, v145, v189
	v_cvt_pk_bf16_f32 v52, v142, v143
	v_cvt_pk_bf16_f32 v53, v144, v145
	v_add_f32_e32 v146, v64, v146
	v_add_f32_e32 v147, v64, v147
	v_add_f32_e32 v148, v64, v148
	v_add_f32_e32 v149, v64, v149
	v_lshlrev_b32_e32 v155, 16, v54
	v_and_b32_e32 v189, 0xffff0000, v54
	v_mul_f32_e32 v146, v146, v155
	v_mul_f32_e32 v147, v147, v189
	v_lshlrev_b32_e32 v155, 16, v55
	v_and_b32_e32 v189, 0xffff0000, v55
	v_mul_f32_e32 v148, v148, v155
	v_mul_f32_e32 v149, v149, v189
	v_cvt_pk_bf16_f32 v54, v146, v147
	v_cvt_pk_bf16_f32 v55, v148, v149
	global_store_dwordx4 v93, v[52:55], s[68:69] offset:64
	s_waitcnt lgkmcnt(4)
	v_mfma_f32_16x16x32_bf16 v[94:97], v[216:219], v[32:35], 0
	v_mfma_f32_16x16x32_bf16 v[94:97], v[220:223], v[36:39], v[94:97]
	v_mfma_f32_16x16x32_bf16 v[94:97], v[224:227], v[40:43], v[94:97]
	v_mfma_f32_16x16x32_bf16 v[94:97], v[228:231], v[44:47], v[94:97]
	ds_read_b128 v[216:219], v87 offset:27200
	ds_read_b128 v[220:223], v87 offset:27264
	ds_read_b128 v[224:227], v87 offset:27328
	ds_read_b128 v[228:231], v87 offset:27392
	s_waitcnt lgkmcnt(4)
	v_mfma_f32_16x16x32_bf16 v[142:145], v[200:203], v[32:35], 0
	v_mfma_f32_16x16x32_bf16 v[142:145], v[204:207], v[36:39], v[142:145]
	v_mfma_f32_16x16x32_bf16 v[142:145], v[208:211], v[40:43], v[142:145]
	v_mfma_f32_16x16x32_bf16 v[142:145], v[212:215], v[44:47], v[142:145]
	v_add_f32_e32 v78, v64, v78
	v_add_f32_e32 v79, v64, v79
	v_add_f32_e32 v80, v64, v80
	v_add_f32_e32 v81, v64, v81
	v_lshlrev_b32_e32 v155, 16, v56
	v_and_b32_e32 v189, 0xffff0000, v56
	v_mul_f32_e32 v78, v78, v155
	v_mul_f32_e32 v79, v79, v189
	v_lshlrev_b32_e32 v155, 16, v57
	v_and_b32_e32 v189, 0xffff0000, v57
	v_mul_f32_e32 v80, v80, v155
	v_mul_f32_e32 v81, v81, v189
	v_cvt_pk_bf16_f32 v56, v78, v79
	v_cvt_pk_bf16_f32 v57, v80, v81
	v_add_f32_e32 v94, v64, v94
	v_add_f32_e32 v95, v64, v95
	v_add_f32_e32 v96, v64, v96
	v_add_f32_e32 v97, v64, v97
	v_lshlrev_b32_e32 v155, 16, v58
	v_and_b32_e32 v189, 0xffff0000, v58
	v_mul_f32_e32 v94, v94, v155
	v_mul_f32_e32 v95, v95, v189
	v_lshlrev_b32_e32 v155, 16, v59
	v_and_b32_e32 v189, 0xffff0000, v59
	v_mul_f32_e32 v96, v96, v155
	v_mul_f32_e32 v97, v97, v189
	v_cvt_pk_bf16_f32 v58, v94, v95
	v_cvt_pk_bf16_f32 v59, v96, v97
	global_store_dwordx4 v93, v[56:59], s[68:69] offset:128
	s_waitcnt lgkmcnt(0)
	v_mfma_f32_16x16x32_bf16 v[146:149], v[216:219], v[32:35], 0
	v_mfma_f32_16x16x32_bf16 v[146:149], v[220:223], v[36:39], v[146:149]
	v_mfma_f32_16x16x32_bf16 v[146:149], v[224:227], v[40:43], v[146:149]
	v_mfma_f32_16x16x32_bf16 v[146:149], v[228:231], v[44:47], v[146:149]
	s_nop 7
	v_add_f32_e32 v142, v64, v142
	v_add_f32_e32 v143, v64, v143
	v_add_f32_e32 v144, v64, v144
	v_add_f32_e32 v145, v64, v145
	v_lshlrev_b32_e32 v155, 16, v60
	v_and_b32_e32 v189, 0xffff0000, v60
	v_mul_f32_e32 v142, v142, v155
	v_mul_f32_e32 v143, v143, v189
	v_lshlrev_b32_e32 v155, 16, v61
	v_and_b32_e32 v189, 0xffff0000, v61
	v_mul_f32_e32 v144, v144, v155
	v_mul_f32_e32 v145, v145, v189
	v_cvt_pk_bf16_f32 v60, v142, v143
	v_cvt_pk_bf16_f32 v61, v144, v145
	v_add_f32_e32 v146, v64, v146
	v_add_f32_e32 v147, v64, v147
	v_add_f32_e32 v148, v64, v148
	v_add_f32_e32 v149, v64, v149
	v_lshlrev_b32_e32 v155, 16, v62
	v_and_b32_e32 v189, 0xffff0000, v62
	v_mul_f32_e32 v146, v146, v155
	v_mul_f32_e32 v147, v147, v189
	v_lshlrev_b32_e32 v155, 16, v63
	v_and_b32_e32 v189, 0xffff0000, v63
	v_mul_f32_e32 v148, v148, v155
	v_mul_f32_e32 v149, v149, v189
	v_cvt_pk_bf16_f32 v62, v146, v147
	v_cvt_pk_bf16_f32 v63, v148, v149
	global_store_dwordx4 v93, v[60:63], s[68:69] offset:192
	s_barrier
	s_mov_b32 s16, s70
	s_cmpk_lt_u32 s16, 0x600
	s_cbranch_scc0 .Lgm_done
.Lgm_loop:
	s_add_u32 s70, s16, s92
	s_min_u32 s71, s70, 0x5ff
	s_mul_hi_u32 s18, s71, 0xaaaaaaab
	s_lshr_b32 s18, s18, 2
	s_mul_i32 s17, s18, 6
	s_sub_u32 s17, s71, s17
	s_mul_i32 s28, s18, 0x3000
	s_add_u32 s4, s6, s28
	s_addc_u32 s5, s7, 0
	s_add_u32 s4, s4, 0x3600000
	s_addc_u32 s5, s5, 0
	global_load_dwordx4 v[4:7], v1, s[4:5]
	global_load_dwordx4 v[8:11], v1, s[4:5] offset:16
	global_load_dwordx4 v[12:15], v1, s[4:5] offset:32
	s_mul_i32 s28, s18, 0x30000
	s_lshl_b32 s29, s17, 8
	s_add_u32 s28, s28, s29
	s_add_u32 s8, s6, s28
	s_addc_u32 s9, s7, 0
	s_add_u32 s14, s8, 0xd200000
	s_addc_u32 s15, s9, 0
	s_add_u32 s8, s8, 0x10200000
	s_addc_u32 s9, s9, 0
	global_load_dwordx4 v[16:19], v85, s[8:9]
	global_load_dwordx4 v[20:23], v85, s[8:9] offset:16
	global_load_dwordx4 v[24:27], v85, s[8:9] offset:32
	global_load_dwordx4 v[28:31], v85, s[8:9] offset:48
	s_lshl_b32 s28, s17, 15
	s_add_u32 s10, s6, s28
	s_addc_u32 s11, s7, 0
	s_add_u32 s10, s10, 0x3200000
	s_addc_u32 s11, s11, 0
	global_load_dwordx4 v[32:35], v90, s[10:11]
	global_load_dwordx4 v[36:39], v90, s[10:11] offset:64
	global_load_dwordx4 v[40:43], v90, s[10:11] offset:128
	global_load_dwordx4 v[44:47], v90, s[10:11] offset:192
	s_lshl_b32 s28, s17, 9
	s_add_u32 s12, s78, s28
	s_addc_u32 s13, s79, 0
	global_load_dword v64, v91, s[12:13]
	global_load_dwordx4 v[48:51], v92, s[14:15]
	global_load_dwordx4 v[52:55], v92, s[14:15] offset:64
	global_load_dwordx4 v[56:59], v92, s[14:15] offset:128
	global_load_dwordx4 v[60:63], v92, s[14:15] offset:192
	s_cmpk_lt_u32 s70, 0x600
	s_cbranch_scc1 .Lgm_kvt_a
	v_readfirstlane_b32 s28, v83
	s_nop 3
	s_cmp_gt_u32 s28, 63
	s_cbranch_scc1 .Lgm_kvt_a
	s_lshr_b32 s28, s2, 6
	s_lshl_b32 s28, s28, 19
	s_bfe_u32 s29, s2, 0x30003
	s_lshl_b32 s29, s29, 16
	s_add_u32 s28, s28, s29
	s_and_b32 s29, s2, 3
	s_lshl_b32 s29, s29, 7
	s_add_u32 s28, s28, s29
	s_add_u32 s28, s28, 0x3e00400
	s_add_u32 s100, s6, s28
	s_addc_u32 s101, s7, 0
	v_lshrrev_b32_e32 v249, 1, v197
	v_lshlrev_b32_e32 v249, 11, v249
	v_and_b32_e32 v248, 1, v197
	v_lshl_add_u32 v249, v248, 9, v249
	s_nop 0
	global_load_dword v248, v249, s[100:101]
.Lgm_kvt_a:
	s_mul_hi_u32 s18, s16, 0xaaaaaaab
	s_lshr_b32 s18, s18, 2
	s_mul_i32 s17, s18, 6
	s_sub_u32 s17, s16, s17
	s_lshl_b32 s28, s17, 9
	v_add_u32_e32 v89, s28, v88
	s_mul_i32 s28, s18, 0x40000
	s_lshl_b32 s29, s17, 8
	s_add_u32 s28, s28, s29
	s_add_u32 s68, s0, s28
	s_addc_u32 s69, s1, 0
	s_waitcnt vmcnt(29)
	ds_read_b128 v[200:203], v89
	ds_read_b128 v[204:207], v89 offset:16
	ds_read_b128 v[208:211], v89 offset:3072
	ds_read_b128 v[212:215], v89 offset:3088
	v_add_f32_e32 v77, v98, v100
	v_add_f32_e32 v154, v99, v101
	v_add_f32_e32 v155, v102, v104
	v_add_f32_e32 v189, v103, v105
	v_add_f32_e32 v77, v77, v155
	v_add_f32_e32 v154, v154, v189
	v_add_f32_e32 v155, v106, v108
	v_add_f32_e32 v189, v107, v109
	v_add_f32_e32 v77, v77, v155
	v_add_f32_e32 v154, v154, v189
	s_nop 1
	v_add_f32_dpp v77, v77, v77 quad_perm:[1,0,3,2] row_mask:0xf bank_mask:0xf
	v_add_f32_dpp v154, v154, v154 quad_perm:[1,0,3,2] row_mask:0xf bank_mask:0xf
	v_mul_f32_e32 v155, 0x3aaaaaab, v77
	v_mul_f32_e32 v155, v155, v155
	s_mov_b32 s28, 0x3aaaaaab
	v_fma_f32 v154, v154, s28, -v155
	v_add_f32_e32 v154, 0x358637bd, v154
	v_rsq_f32_e32 v154, v154
	ds_read_b128 v[216:219], v89 offset:32
	ds_read_b128 v[220:223], v89 offset:48
	ds_read_b128 v[224:227], v89 offset:3104
	ds_read_b128 v[228:231], v89 offset:3120
	s_waitcnt lgkmcnt(4)
	v_lshlrev_b32_e32 v155, 16, v110
	v_and_b32_e32 v189, 0xffff0000, v110
	v_fmac_f32_e32 v155, 0xbaaaaaab, v77
	v_fmac_f32_e32 v189, 0xbaaaaaab, v77
	v_mul_f32_e32 v155, v155, v154
	v_mul_f32_e32 v189, v189, v154
	v_fma_f32 v155, v200, v155, v208
	v_fma_f32 v189, v201, v189, v209
	v_cvt_pk_bf16_f32 v110, v155, v189
	ds_write_b16 v86, v110
	ds_write_b16_d16_hi v86, v110 offset:272
	v_lshlrev_b32_e32 v155, 16, v111
	v_and_b32_e32 v189, 0xffff0000, v111
	v_fmac_f32_e32 v155, 0xbaaaaaab, v77
	v_fmac_f32_e32 v189, 0xbaaaaaab, v77
	v_mul_f32_e32 v155, v155, v154
	v_mul_f32_e32 v189, v189, v154
	v_fma_f32 v155, v202, v155, v210
	v_fma_f32 v189, v203, v189, v211
	v_cvt_pk_bf16_f32 v111, v155, v189
	ds_write_b16 v86, v111 offset:544
	ds_write_b16_d16_hi v86, v111 offset:816
	v_lshlrev_b32_e32 v155, 16, v112
	v_and_b32_e32 v189, 0xffff0000, v112
	v_fmac_f32_e32 v155, 0xbaaaaaab, v77
	v_fmac_f32_e32 v189, 0xbaaaaaab, v77
	v_mul_f32_e32 v155, v155, v154
	v_mul_f32_e32 v189, v189, v154
	v_fma_f32 v155, v204, v155, v212
	v_fma_f32 v189, v205, v189, v213
	v_cvt_pk_bf16_f32 v112, v155, v189
	ds_write_b16 v86, v112 offset:1088
	ds_write_b16_d16_hi v86, v112 offset:1360
	v_lshlrev_b32_e32 v155, 16, v113
	v_and_b32_e32 v189, 0xffff0000, v113
	v_fmac_f32_e32 v155, 0xbaaaaaab, v77
	v_fmac_f32_e32 v189, 0xbaaaaaab, v77
	v_mul_f32_e32 v155, v155, v154
	v_mul_f32_e32 v189, v189, v154
	v_fma_f32 v155, v206, v155, v214
	v_fma_f32 v189, v207, v189, v215
	v_cvt_pk_bf16_f32 v113, v155, v189
	ds_write_b16 v86, v113 offset:1632
	ds_write_b16_d16_hi v86, v113 offset:1904
	ds_read_b128 v[200:203], v89 offset:64
	ds_read_b128 v[204:207], v89 offset:80
	ds_read_b128 v[208:211], v89 offset:3136
	ds_read_b128 v[212:215], v89 offset:3152
	s_waitcnt lgkmcnt(4)
	v_lshlrev_b32_e32 v155, 16, v114
	v_and_b32_e32 v189, 0xffff0000, v114
	v_fmac_f32_e32 v155, 0xbaaaaaab, v77
	v_fmac_f32_e32 v189, 0xbaaaaaab, v77
	v_mul_f32_e32 v155, v155, v154
	v_mul_f32_e32 v189, v189, v154
	v_fma_f32 v155, v216, v155, v224
	v_fma_f32 v189, v217, v189, v225
	v_cvt_pk_bf16_f32 v114, v155, v189
	ds_write_b16 v86, v114 offset:2176
	ds_write_b16_d16_hi v86, v114 offset:2448
	v_lshlrev_b32_e32 v155, 16, v115
	v_and_b32_e32 v189, 0xffff0000, v115
	v_fmac_f32_e32 v155, 0xbaaaaaab, v77
	v_fmac_f32_e32 v189, 0xbaaaaaab, v77
	v_mul_f32_e32 v155, v155, v154
	v_mul_f32_e32 v189, v189, v154
	v_fma_f32 v155, v218, v155, v226
	v_fma_f32 v189, v219, v189, v227
	v_cvt_pk_bf16_f32 v115, v155, v189
	ds_write_b16 v86, v115 offset:2720
	ds_write_b16_d16_hi v86, v115 offset:2992
	v_lshlrev_b32_e32 v155, 16, v116
	v_and_b32_e32 v189, 0xffff0000, v116
	v_fmac_f32_e32 v155, 0xbaaaaaab, v77
	v_fmac_f32_e32 v189, 0xbaaaaaab, v77
	v_mul_f32_e32 v155, v155, v154
	v_mul_f32_e32 v189, v189, v154
	v_fma_f32 v155, v220, v155, v228
	v_fma_f32 v189, v221, v189, v229
	v_cvt_pk_bf16_f32 v116, v155, v189
	ds_write_b16 v86, v116 offset:3264
	ds_write_b16_d16_hi v86, v116 offset:3536
	v_lshlrev_b32_e32 v155, 16, v117
	v_and_b32_e32 v189, 0xffff0000, v117
	v_fmac_f32_e32 v155, 0xbaaaaaab, v77
	v_fmac_f32_e32 v189, 0xbaaaaaab, v77
	v_mul_f32_e32 v155, v155, v154
	v_mul_f32_e32 v189, v189, v154
	v_fma_f32 v155, v222, v155, v230
	v_fma_f32 v189, v223, v189, v231
	v_cvt_pk_bf16_f32 v117, v155, v189
	ds_write_b16 v86, v117 offset:3808
	ds_write_b16_d16_hi v86, v117 offset:4080
	ds_read_b128 v[216:219], v89 offset:96
	ds_read_b128 v[220:223], v89 offset:112
	ds_read_b128 v[224:227], v89 offset:3168
	ds_read_b128 v[228:231], v89 offset:3184
	s_waitcnt lgkmcnt(4)
	v_lshlrev_b32_e32 v155, 16, v118
	v_and_b32_e32 v189, 0xffff0000, v118
	v_fmac_f32_e32 v155, 0xbaaaaaab, v77
	v_fmac_f32_e32 v189, 0xbaaaaaab, v77
	v_mul_f32_e32 v155, v155, v154
	v_mul_f32_e32 v189, v189, v154
	v_fma_f32 v155, v200, v155, v208
	v_fma_f32 v189, v201, v189, v209
	v_cvt_pk_bf16_f32 v118, v155, v189
	ds_write_b16 v86, v118 offset:4352
	ds_write_b16_d16_hi v86, v118 offset:4624
	v_lshlrev_b32_e32 v155, 16, v119
	v_and_b32_e32 v189, 0xffff0000, v119
	v_fmac_f32_e32 v155, 0xbaaaaaab, v77
	v_fmac_f32_e32 v189, 0xbaaaaaab, v77
	v_mul_f32_e32 v155, v155, v154
	v_mul_f32_e32 v189, v189, v154
	v_fma_f32 v155, v202, v155, v210
	v_fma_f32 v189, v203, v189, v211
	v_cvt_pk_bf16_f32 v119, v155, v189
	ds_write_b16 v86, v119 offset:4896
	ds_write_b16_d16_hi v86, v119 offset:5168
	v_lshlrev_b32_e32 v155, 16, v120
	v_and_b32_e32 v189, 0xffff0000, v120
	v_fmac_f32_e32 v155, 0xbaaaaaab, v77
	v_fmac_f32_e32 v189, 0xbaaaaaab, v77
	v_mul_f32_e32 v155, v155, v154
	v_mul_f32_e32 v189, v189, v154
	v_fma_f32 v155, v204, v155, v212
	v_fma_f32 v189, v205, v189, v213
	v_cvt_pk_bf16_f32 v120, v155, v189
	ds_write_b16 v86, v120 offset:5440
	ds_write_b16_d16_hi v86, v120 offset:5712
	v_lshlrev_b32_e32 v155, 16, v121
	v_and_b32_e32 v189, 0xffff0000, v121
	v_fmac_f32_e32 v155, 0xbaaaaaab, v77
	v_fmac_f32_e32 v189, 0xbaaaaaab, v77
	v_mul_f32_e32 v155, v155, v154
	v_mul_f32_e32 v189, v189, v154
	v_fma_f32 v155, v206, v155, v214
	v_fma_f32 v189, v207, v189, v215
	v_cvt_pk_bf16_f32 v121, v155, v189
	ds_write_b16 v86, v121 offset:5984
	ds_write_b16_d16_hi v86, v121 offset:6256
	s_waitcnt lgkmcnt(0)
	v_lshlrev_b32_e32 v155, 16, v122
	v_and_b32_e32 v189, 0xffff0000, v122
	v_fmac_f32_e32 v155, 0xbaaaaaab, v77
	v_fmac_f32_e32 v189, 0xbaaaaaab, v77
	v_mul_f32_e32 v155, v155, v154
	v_mul_f32_e32 v189, v189, v154
	v_fma_f32 v155, v216, v155, v224
	v_fma_f32 v189, v217, v189, v225
	v_cvt_pk_bf16_f32 v122, v155, v189
	ds_write_b16 v86, v122 offset:6528
	ds_write_b16_d16_hi v86, v122 offset:6800
	v_lshlrev_b32_e32 v155, 16, v123
	v_and_b32_e32 v189, 0xffff0000, v123
	v_fmac_f32_e32 v155, 0xbaaaaaab, v77
	v_fmac_f32_e32 v189, 0xbaaaaaab, v77
	v_mul_f32_e32 v155, v155, v154
	v_mul_f32_e32 v189, v189, v154
	v_fma_f32 v155, v218, v155, v226
	v_fma_f32 v189, v219, v189, v227
	v_cvt_pk_bf16_f32 v123, v155, v189
	ds_write_b16 v86, v123 offset:7072
	ds_write_b16_d16_hi v86, v123 offset:7344
	v_lshlrev_b32_e32 v155, 16, v124
	v_and_b32_e32 v189, 0xffff0000, v124
	v_fmac_f32_e32 v155, 0xbaaaaaab, v77
	v_fmac_f32_e32 v189, 0xbaaaaaab, v77
	v_mul_f32_e32 v155, v155, v154
	v_mul_f32_e32 v189, v189, v154
	v_fma_f32 v155, v220, v155, v228
	v_fma_f32 v189, v221, v189, v229
	v_cvt_pk_bf16_f32 v124, v155, v189
	ds_write_b16 v86, v124 offset:7616
	ds_write_b16_d16_hi v86, v124 offset:7888
	v_lshlrev_b32_e32 v155, 16, v125
	v_and_b32_e32 v189, 0xffff0000, v125
	v_fmac_f32_e32 v155, 0xbaaaaaab, v77
	v_fmac_f32_e32 v189, 0xbaaaaaab, v77
	v_mul_f32_e32 v155, v155, v154
	v_mul_f32_e32 v189, v189, v154
	v_fma_f32 v155, v222, v155, v230
	v_fma_f32 v189, v223, v189, v231
	v_cvt_pk_bf16_f32 v125, v155, v189
	ds_write_b16 v86, v125 offset:8160
	ds_write_b16_d16_hi v86, v125 offset:8432
	s_waitcnt lgkmcnt(0)
	s_barrier
	s_waitcnt vmcnt(20)
	ds_read_b128 v[200:203], v87 offset:0
	ds_read_b128 v[204:207], v87 offset:64
	ds_read_b128 v[208:211], v87 offset:128
	ds_read_b128 v[212:215], v87 offset:192
	ds_read_b128 v[216:219], v87 offset:1088
	ds_read_b128 v[220:223], v87 offset:1152
	ds_read_b128 v[224:227], v87 offset:1216
	ds_read_b128 v[228:231], v87 offset:1280
	s_waitcnt lgkmcnt(4)
	v_mfma_f32_16x16x32_bf16 v[78:81], v[200:203], v[126:129], 0
	v_mfma_f32_16x16x32_bf16 v[78:81], v[204:207], v[130:133], v[78:81]
	v_mfma_f32_16x16x32_bf16 v[78:81], v[208:211], v[134:137], v[78:81]
	v_mfma_f32_16x16x32_bf16 v[78:81], v[212:215], v[138:141], v[78:81]
	ds_read_b128 v[200:203], v87 offset:8704
	ds_read_b128 v[204:207], v87 offset:8768
	ds_read_b128 v[208:211], v87 offset:8832
	ds_read_b128 v[212:215], v87 offset:8896
	s_waitcnt lgkmcnt(4)
	v_mfma_f32_16x16x32_bf16 v[94:97], v[216:219], v[126:129], 0
	v_mfma_f32_16x16x32_bf16 v[94:97], v[220:223], v[130:133], v[94:97]
	v_mfma_f32_16x16x32_bf16 v[94:97], v[224:227], v[134:137], v[94:97]
	v_mfma_f32_16x16x32_bf16 v[94:97], v[228:231], v[138:141], v[94:97]
	ds_read_b128 v[216:219], v87 offset:9792
	ds_read_b128 v[220:223], v87 offset:9856
	ds_read_b128 v[224:227], v87 offset:9920
	ds_read_b128 v[228:231], v87 offset:9984
	s_waitcnt lgkmcnt(4)
	v_mfma_f32_16x16x32_bf16 v[142:145], v[200:203], v[126:129], 0
	v_mfma_f32_16x16x32_bf16 v[142:145], v[204:207], v[130:133], v[142:145]
	v_mfma_f32_16x16x32_bf16 v[142:145], v[208:211], v[134:137], v[142:145]
	v_mfma_f32_16x16x32_bf16 v[142:145], v[212:215], v[138:141], v[142:145]
	ds_read_b128 v[200:203], v87 offset:17408
	ds_read_b128 v[204:207], v87 offset:17472
	ds_read_b128 v[208:211], v87 offset:17536
	ds_read_b128 v[212:215], v87 offset:17600
	v_add_f32_e32 v78, v188, v78
	v_add_f32_e32 v79, v188, v79
	v_add_f32_e32 v80, v188, v80
	v_add_f32_e32 v81, v188, v81
	v_lshlrev_b32_e32 v155, 16, v172
	v_and_b32_e32 v189, 0xffff0000, v172
	v_mul_f32_e32 v78, v78, v155
	v_mul_f32_e32 v79, v79, v189
	v_lshlrev_b32_e32 v155, 16, v173
	v_and_b32_e32 v189, 0xffff0000, v173
	v_mul_f32_e32 v80, v80, v155
	v_mul_f32_e32 v81, v81, v189
	v_cvt_pk_bf16_f32 v172, v78, v79
	v_cvt_pk_bf16_f32 v173, v80, v81
	v_add_f32_e32 v94, v188, v94
	v_add_f32_e32 v95, v188, v95
	v_add_f32_e32 v96, v188, v96
	v_add_f32_e32 v97, v188, v97
	v_lshlrev_b32_e32 v155, 16, v174
	v_and_b32_e32 v189, 0xffff0000, v174
	v_mul_f32_e32 v94, v94, v155
	v_mul_f32_e32 v95, v95, v189
	v_lshlrev_b32_e32 v155, 16, v175
	v_and_b32_e32 v189, 0xffff0000, v175
	v_mul_f32_e32 v96, v96, v155
	v_mul_f32_e32 v97, v97, v189
	v_cvt_pk_bf16_f32 v174, v94, v95
	v_cvt_pk_bf16_f32 v175, v96, v97
	global_store_dwordx4 v93, v[172:175], s[68:69]
	s_waitcnt lgkmcnt(4)
	v_mfma_f32_16x16x32_bf16 v[146:149], v[216:219], v[126:129], 0
	v_mfma_f32_16x16x32_bf16 v[146:149], v[220:223], v[130:133], v[146:149]
	v_mfma_f32_16x16x32_bf16 v[146:149], v[224:227], v[134:137], v[146:149]
	v_mfma_f32_16x16x32_bf16 v[146:149], v[228:231], v[138:141], v[146:149]
	ds_read_b128 v[216:219], v87 offset:18496
	ds_read_b128 v[220:223], v87 offset:18560
	ds_read_b128 v[224:227], v87 offset:18624
	ds_read_b128 v[228:231], v87 offset:18688
	s_waitcnt lgkmcnt(4)
	v_mfma_f32_16x16x32_bf16 v[78:81], v[200:203], v[126:129], 0
	v_mfma_f32_16x16x32_bf16 v[78:81], v[204:207], v[130:133], v[78:81]
	v_mfma_f32_16x16x32_bf16 v[78:81], v[208:211], v[134:137], v[78:81]
	v_mfma_f32_16x16x32_bf16 v[78:81], v[212:215], v[138:141], v[78:81]
	ds_read_b128 v[200:203], v87 offset:26112
	ds_read_b128 v[204:207], v87 offset:26176
	ds_read_b128 v[208:211], v87 offset:26240
	ds_read_b128 v[212:215], v87 offset:26304
	v_add_f32_e32 v142, v188, v142
	v_add_f32_e32 v143, v188, v143
	v_add_f32_e32 v144, v188, v144
	v_add_f32_e32 v145, v188, v145
	v_lshlrev_b32_e32 v155, 16, v176
	v_and_b32_e32 v189, 0xffff0000, v176
	v_mul_f32_e32 v142, v142, v155
	v_mul_f32_e32 v143, v143, v189
	v_lshlrev_b32_e32 v155, 16, v177
	v_and_b32_e32 v189, 0xffff0000, v177
	v_mul_f32_e32 v144, v144, v155
	v_mul_f32_e32 v145, v145, v189
	v_cvt_pk_bf16_f32 v176, v142, v143
	v_cvt_pk_bf16_f32 v177, v144, v145
	v_add_f32_e32 v146, v188, v146
	v_add_f32_e32 v147, v188, v147
	v_add_f32_e32 v148, v188, v148
	v_add_f32_e32 v149, v188, v149
	v_lshlrev_b32_e32 v155, 16, v178
	v_and_b32_e32 v189, 0xffff0000, v178
	v_mul_f32_e32 v146, v146, v155
	v_mul_f32_e32 v147, v147, v189
	v_lshlrev_b32_e32 v155, 16, v179
	v_and_b32_e32 v189, 0xffff0000, v179
	v_mul_f32_e32 v148, v148, v155
	v_mul_f32_e32 v149, v149, v189
	v_cvt_pk_bf16_f32 v178, v146, v147
	v_cvt_pk_bf16_f32 v179, v148, v149
	global_store_dwordx4 v93, v[176:179], s[68:69] offset:64
	s_waitcnt lgkmcnt(4)
	v_mfma_f32_16x16x32_bf16 v[94:97], v[216:219], v[126:129], 0
	v_mfma_f32_16x16x32_bf16 v[94:97], v[220:223], v[130:133], v[94:97]
	v_mfma_f32_16x16x32_bf16 v[94:97], v[224:227], v[134:137], v[94:97]
	v_mfma_f32_16x16x32_bf16 v[94:97], v[228:231], v[138:141], v[94:97]
	ds_read_b128 v[216:219], v87 offset:27200
	ds_read_b128 v[220:223], v87 offset:27264
	ds_read_b128 v[224:227], v87 offset:27328
	ds_read_b128 v[228:231], v87 offset:27392
	s_waitcnt lgkmcnt(4)
	v_mfma_f32_16x16x32_bf16 v[142:145], v[200:203], v[126:129], 0
	v_mfma_f32_16x16x32_bf16 v[142:145], v[204:207], v[130:133], v[142:145]
	v_mfma_f32_16x16x32_bf16 v[142:145], v[208:211], v[134:137], v[142:145]
	v_mfma_f32_16x16x32_bf16 v[142:145], v[212:215], v[138:141], v[142:145]
	v_add_f32_e32 v78, v188, v78
	v_add_f32_e32 v79, v188, v79
	v_add_f32_e32 v80, v188, v80
	v_add_f32_e32 v81, v188, v81
	v_lshlrev_b32_e32 v155, 16, v180
	v_and_b32_e32 v189, 0xffff0000, v180
	v_mul_f32_e32 v78, v78, v155
	v_mul_f32_e32 v79, v79, v189
	v_lshlrev_b32_e32 v155, 16, v181
	v_and_b32_e32 v189, 0xffff0000, v181
	v_mul_f32_e32 v80, v80, v155
	v_mul_f32_e32 v81, v81, v189
	v_cvt_pk_bf16_f32 v180, v78, v79
	v_cvt_pk_bf16_f32 v181, v80, v81
	v_add_f32_e32 v94, v188, v94
	v_add_f32_e32 v95, v188, v95
	v_add_f32_e32 v96, v188, v96
	v_add_f32_e32 v97, v188, v97
	v_lshlrev_b32_e32 v155, 16, v182
	v_and_b32_e32 v189, 0xffff0000, v182
	v_mul_f32_e32 v94, v94, v155
	v_mul_f32_e32 v95, v95, v189
	v_lshlrev_b32_e32 v155, 16, v183
	v_and_b32_e32 v189, 0xffff0000, v183
	v_mul_f32_e32 v96, v96, v155
	v_mul_f32_e32 v97, v97, v189
	v_cvt_pk_bf16_f32 v182, v94, v95
	v_cvt_pk_bf16_f32 v183, v96, v97
	global_store_dwordx4 v93, v[180:183], s[68:69] offset:128
	s_waitcnt lgkmcnt(0)
	v_mfma_f32_16x16x32_bf16 v[146:149], v[216:219], v[126:129], 0
	v_mfma_f32_16x16x32_bf16 v[146:149], v[220:223], v[130:133], v[146:149]
	v_mfma_f32_16x16x32_bf16 v[146:149], v[224:227], v[134:137], v[146:149]
	v_mfma_f32_16x16x32_bf16 v[146:149], v[228:231], v[138:141], v[146:149]
	s_nop 7
	v_add_f32_e32 v142, v188, v142
	v_add_f32_e32 v143, v188, v143
	v_add_f32_e32 v144, v188, v144
	v_add_f32_e32 v145, v188, v145
	v_lshlrev_b32_e32 v155, 16, v184
	v_and_b32_e32 v189, 0xffff0000, v184
	v_mul_f32_e32 v142, v142, v155
	v_mul_f32_e32 v143, v143, v189
	v_lshlrev_b32_e32 v155, 16, v185
	v_and_b32_e32 v189, 0xffff0000, v185
	v_mul_f32_e32 v144, v144, v155
	v_mul_f32_e32 v145, v145, v189
	v_cvt_pk_bf16_f32 v184, v142, v143
	v_cvt_pk_bf16_f32 v185, v144, v145
	v_add_f32_e32 v146, v188, v146
	v_add_f32_e32 v147, v188, v147
	v_add_f32_e32 v148, v188, v148
	v_add_f32_e32 v149, v188, v149
	v_lshlrev_b32_e32 v155, 16, v186
	v_and_b32_e32 v189, 0xffff0000, v186
	v_mul_f32_e32 v146, v146, v155
	v_mul_f32_e32 v147, v147, v189
	v_lshlrev_b32_e32 v155, 16, v187
	v_and_b32_e32 v189, 0xffff0000, v187
	v_mul_f32_e32 v148, v148, v155
	v_mul_f32_e32 v149, v149, v189
	v_cvt_pk_bf16_f32 v186, v146, v147
	v_cvt_pk_bf16_f32 v187, v148, v149
	global_store_dwordx4 v93, v[184:187], s[68:69] offset:192
	s_barrier
	s_mov_b32 s16, s70
	s_cmpk_lt_u32 s16, 0x600
	s_cbranch_scc0 .Lgm_done
	s_add_u32 s70, s16, s92
	s_min_u32 s71, s70, 0x5ff
	s_mul_hi_u32 s18, s71, 0xaaaaaaab
	s_lshr_b32 s18, s18, 2
	s_mul_i32 s17, s18, 6
	s_sub_u32 s17, s71, s17
	s_mul_i32 s28, s18, 0x3000
	s_add_u32 s4, s6, s28
	s_addc_u32 s5, s7, 0
	s_add_u32 s4, s4, 0x3600000
	s_addc_u32 s5, s5, 0
	global_load_dwordx4 v[98:101], v1, s[4:5]
	global_load_dwordx4 v[102:105], v1, s[4:5] offset:16
	global_load_dwordx4 v[106:109], v1, s[4:5] offset:32
	s_mul_i32 s28, s18, 0x30000
	s_lshl_b32 s29, s17, 8
	s_add_u32 s28, s28, s29
	s_add_u32 s8, s6, s28
	s_addc_u32 s9, s7, 0
	s_add_u32 s14, s8, 0xd200000
	s_addc_u32 s15, s9, 0
	s_add_u32 s8, s8, 0x10200000
	s_addc_u32 s9, s9, 0
	global_load_dwordx4 v[110:113], v85, s[8:9]
	global_load_dwordx4 v[114:117], v85, s[8:9] offset:16
	global_load_dwordx4 v[118:121], v85, s[8:9] offset:32
	global_load_dwordx4 v[122:125], v85, s[8:9] offset:48
	s_lshl_b32 s28, s17, 15
	s_add_u32 s10, s6, s28
	s_addc_u32 s11, s7, 0
	s_add_u32 s10, s10, 0x3200000
	s_addc_u32 s11, s11, 0
	global_load_dwordx4 v[126:129], v90, s[10:11]
	global_load_dwordx4 v[130:133], v90, s[10:11] offset:64
	global_load_dwordx4 v[134:137], v90, s[10:11] offset:128
	global_load_dwordx4 v[138:141], v90, s[10:11] offset:192
	s_lshl_b32 s28, s17, 9
	s_add_u32 s12, s78, s28
	s_addc_u32 s13, s79, 0
	global_load_dword v188, v91, s[12:13]
	global_load_dwordx4 v[172:175], v92, s[14:15]
	global_load_dwordx4 v[176:179], v92, s[14:15] offset:64
	global_load_dwordx4 v[180:183], v92, s[14:15] offset:128
	global_load_dwordx4 v[184:187], v92, s[14:15] offset:192
	s_cmpk_lt_u32 s70, 0x600
	s_cbranch_scc1 .Lgm_kvt_b
	v_readfirstlane_b32 s28, v83
	s_nop 3
	s_cmp_gt_u32 s28, 63
	s_cbranch_scc1 .Lgm_kvt_b
	s_lshr_b32 s28, s2, 6
	s_lshl_b32 s28, s28, 19
	s_bfe_u32 s29, s2, 0x30003
	s_lshl_b32 s29, s29, 16
	s_add_u32 s28, s28, s29
	s_and_b32 s29, s2, 3
	s_lshl_b32 s29, s29, 7
	s_add_u32 s28, s28, s29
	s_add_u32 s28, s28, 0x3e00400
	s_add_u32 s100, s6, s28
	s_addc_u32 s101, s7, 0
	v_lshrrev_b32_e32 v249, 1, v197
	v_lshlrev_b32_e32 v249, 11, v249
	v_and_b32_e32 v248, 1, v197
	v_lshl_add_u32 v249, v248, 9, v249
	s_nop 0
	global_load_dword v248, v249, s[100:101]
.Lgm_kvt_b:
	s_mul_hi_u32 s18, s16, 0xaaaaaaab
	s_lshr_b32 s18, s18, 2
	s_mul_i32 s17, s18, 6
	s_sub_u32 s17, s16, s17
	s_lshl_b32 s28, s17, 9
	v_add_u32_e32 v89, s28, v88
	s_mul_i32 s28, s18, 0x40000
	s_lshl_b32 s29, s17, 8
	s_add_u32 s28, s28, s29
	s_add_u32 s68, s0, s28
	s_addc_u32 s69, s1, 0
	s_waitcnt vmcnt(29)
	ds_read_b128 v[200:203], v89
	ds_read_b128 v[204:207], v89 offset:16
	ds_read_b128 v[208:211], v89 offset:3072
	ds_read_b128 v[212:215], v89 offset:3088
	v_add_f32_e32 v77, v4, v6
	v_add_f32_e32 v154, v5, v7
	v_add_f32_e32 v155, v8, v10
	v_add_f32_e32 v189, v9, v11
	v_add_f32_e32 v77, v77, v155
	v_add_f32_e32 v154, v154, v189
	v_add_f32_e32 v155, v12, v14
	v_add_f32_e32 v189, v13, v15
	v_add_f32_e32 v77, v77, v155
	v_add_f32_e32 v154, v154, v189
	s_nop 1
	v_add_f32_dpp v77, v77, v77 quad_perm:[1,0,3,2] row_mask:0xf bank_mask:0xf
	v_add_f32_dpp v154, v154, v154 quad_perm:[1,0,3,2] row_mask:0xf bank_mask:0xf
	v_mul_f32_e32 v155, 0x3aaaaaab, v77
	v_mul_f32_e32 v155, v155, v155
	s_mov_b32 s28, 0x3aaaaaab
	v_fma_f32 v154, v154, s28, -v155
	v_add_f32_e32 v154, 0x358637bd, v154
	v_rsq_f32_e32 v154, v154
	ds_read_b128 v[216:219], v89 offset:32
	ds_read_b128 v[220:223], v89 offset:48
	ds_read_b128 v[224:227], v89 offset:3104
	ds_read_b128 v[228:231], v89 offset:3120
	s_waitcnt lgkmcnt(4)
	v_lshlrev_b32_e32 v155, 16, v16
	v_and_b32_e32 v189, 0xffff0000, v16
	v_fmac_f32_e32 v155, 0xbaaaaaab, v77
	v_fmac_f32_e32 v189, 0xbaaaaaab, v77
	v_mul_f32_e32 v155, v155, v154
	v_mul_f32_e32 v189, v189, v154
	v_fma_f32 v155, v200, v155, v208
	v_fma_f32 v189, v201, v189, v209
	v_cvt_pk_bf16_f32 v16, v155, v189
	ds_write_b16 v86, v16
	ds_write_b16_d16_hi v86, v16 offset:272
	v_lshlrev_b32_e32 v155, 16, v17
	v_and_b32_e32 v189, 0xffff0000, v17
	v_fmac_f32_e32 v155, 0xbaaaaaab, v77
	v_fmac_f32_e32 v189, 0xbaaaaaab, v77
	v_mul_f32_e32 v155, v155, v154
	v_mul_f32_e32 v189, v189, v154
	v_fma_f32 v155, v202, v155, v210
	v_fma_f32 v189, v203, v189, v211
	v_cvt_pk_bf16_f32 v17, v155, v189
	ds_write_b16 v86, v17 offset:544
	ds_write_b16_d16_hi v86, v17 offset:816
	v_lshlrev_b32_e32 v155, 16, v18
	v_and_b32_e32 v189, 0xffff0000, v18
	v_fmac_f32_e32 v155, 0xbaaaaaab, v77
	v_fmac_f32_e32 v189, 0xbaaaaaab, v77
	v_mul_f32_e32 v155, v155, v154
	v_mul_f32_e32 v189, v189, v154
	v_fma_f32 v155, v204, v155, v212
	v_fma_f32 v189, v205, v189, v213
	v_cvt_pk_bf16_f32 v18, v155, v189
	ds_write_b16 v86, v18 offset:1088
	ds_write_b16_d16_hi v86, v18 offset:1360
	v_lshlrev_b32_e32 v155, 16, v19
	v_and_b32_e32 v189, 0xffff0000, v19
	v_fmac_f32_e32 v155, 0xbaaaaaab, v77
	v_fmac_f32_e32 v189, 0xbaaaaaab, v77
	v_mul_f32_e32 v155, v155, v154
	v_mul_f32_e32 v189, v189, v154
	v_fma_f32 v155, v206, v155, v214
	v_fma_f32 v189, v207, v189, v215
	v_cvt_pk_bf16_f32 v19, v155, v189
	ds_write_b16 v86, v19 offset:1632
	ds_write_b16_d16_hi v86, v19 offset:1904
	ds_read_b128 v[200:203], v89 offset:64
	ds_read_b128 v[204:207], v89 offset:80
	ds_read_b128 v[208:211], v89 offset:3136
	ds_read_b128 v[212:215], v89 offset:3152
	s_waitcnt lgkmcnt(4)
	v_lshlrev_b32_e32 v155, 16, v20
	v_and_b32_e32 v189, 0xffff0000, v20
	v_fmac_f32_e32 v155, 0xbaaaaaab, v77
	v_fmac_f32_e32 v189, 0xbaaaaaab, v77
	v_mul_f32_e32 v155, v155, v154
	v_mul_f32_e32 v189, v189, v154
	v_fma_f32 v155, v216, v155, v224
	v_fma_f32 v189, v217, v189, v225
	v_cvt_pk_bf16_f32 v20, v155, v189
	ds_write_b16 v86, v20 offset:2176
	ds_write_b16_d16_hi v86, v20 offset:2448
	v_lshlrev_b32_e32 v155, 16, v21
	v_and_b32_e32 v189, 0xffff0000, v21
	v_fmac_f32_e32 v155, 0xbaaaaaab, v77
	v_fmac_f32_e32 v189, 0xbaaaaaab, v77
	v_mul_f32_e32 v155, v155, v154
	v_mul_f32_e32 v189, v189, v154
	v_fma_f32 v155, v218, v155, v226
	v_fma_f32 v189, v219, v189, v227
	v_cvt_pk_bf16_f32 v21, v155, v189
	ds_write_b16 v86, v21 offset:2720
	ds_write_b16_d16_hi v86, v21 offset:2992
	v_lshlrev_b32_e32 v155, 16, v22
	v_and_b32_e32 v189, 0xffff0000, v22
	v_fmac_f32_e32 v155, 0xbaaaaaab, v77
	v_fmac_f32_e32 v189, 0xbaaaaaab, v77
	v_mul_f32_e32 v155, v155, v154
	v_mul_f32_e32 v189, v189, v154
	v_fma_f32 v155, v220, v155, v228
	v_fma_f32 v189, v221, v189, v229
	v_cvt_pk_bf16_f32 v22, v155, v189
	ds_write_b16 v86, v22 offset:3264
	ds_write_b16_d16_hi v86, v22 offset:3536
	v_lshlrev_b32_e32 v155, 16, v23
	v_and_b32_e32 v189, 0xffff0000, v23
	v_fmac_f32_e32 v155, 0xbaaaaaab, v77
	v_fmac_f32_e32 v189, 0xbaaaaaab, v77
	v_mul_f32_e32 v155, v155, v154
	v_mul_f32_e32 v189, v189, v154
	v_fma_f32 v155, v222, v155, v230
	v_fma_f32 v189, v223, v189, v231
	v_cvt_pk_bf16_f32 v23, v155, v189
	ds_write_b16 v86, v23 offset:3808
	ds_write_b16_d16_hi v86, v23 offset:4080
	ds_read_b128 v[216:219], v89 offset:96
	ds_read_b128 v[220:223], v89 offset:112
	ds_read_b128 v[224:227], v89 offset:3168
	ds_read_b128 v[228:231], v89 offset:3184
	s_waitcnt lgkmcnt(4)
	v_lshlrev_b32_e32 v155, 16, v24
	v_and_b32_e32 v189, 0xffff0000, v24
	v_fmac_f32_e32 v155, 0xbaaaaaab, v77
	v_fmac_f32_e32 v189, 0xbaaaaaab, v77
	v_mul_f32_e32 v155, v155, v154
	v_mul_f32_e32 v189, v189, v154
	v_fma_f32 v155, v200, v155, v208
	v_fma_f32 v189, v201, v189, v209
	v_cvt_pk_bf16_f32 v24, v155, v189
	ds_write_b16 v86, v24 offset:4352
	ds_write_b16_d16_hi v86, v24 offset:4624
	v_lshlrev_b32_e32 v155, 16, v25
	v_and_b32_e32 v189, 0xffff0000, v25
	v_fmac_f32_e32 v155, 0xbaaaaaab, v77
	v_fmac_f32_e32 v189, 0xbaaaaaab, v77
	v_mul_f32_e32 v155, v155, v154
	v_mul_f32_e32 v189, v189, v154
	v_fma_f32 v155, v202, v155, v210
	v_fma_f32 v189, v203, v189, v211
	v_cvt_pk_bf16_f32 v25, v155, v189
	ds_write_b16 v86, v25 offset:4896
	ds_write_b16_d16_hi v86, v25 offset:5168
	v_lshlrev_b32_e32 v155, 16, v26
	v_and_b32_e32 v189, 0xffff0000, v26
	v_fmac_f32_e32 v155, 0xbaaaaaab, v77
	v_fmac_f32_e32 v189, 0xbaaaaaab, v77
	v_mul_f32_e32 v155, v155, v154
	v_mul_f32_e32 v189, v189, v154
	v_fma_f32 v155, v204, v155, v212
	v_fma_f32 v189, v205, v189, v213
	v_cvt_pk_bf16_f32 v26, v155, v189
	ds_write_b16 v86, v26 offset:5440
	ds_write_b16_d16_hi v86, v26 offset:5712
	v_lshlrev_b32_e32 v155, 16, v27
	v_and_b32_e32 v189, 0xffff0000, v27
	v_fmac_f32_e32 v155, 0xbaaaaaab, v77
	v_fmac_f32_e32 v189, 0xbaaaaaab, v77
	v_mul_f32_e32 v155, v155, v154
	v_mul_f32_e32 v189, v189, v154
	v_fma_f32 v155, v206, v155, v214
	v_fma_f32 v189, v207, v189, v215
	v_cvt_pk_bf16_f32 v27, v155, v189
	ds_write_b16 v86, v27 offset:5984
	ds_write_b16_d16_hi v86, v27 offset:6256
	s_waitcnt lgkmcnt(0)
	v_lshlrev_b32_e32 v155, 16, v28
	v_and_b32_e32 v189, 0xffff0000, v28
	v_fmac_f32_e32 v155, 0xbaaaaaab, v77
	v_fmac_f32_e32 v189, 0xbaaaaaab, v77
	v_mul_f32_e32 v155, v155, v154
	v_mul_f32_e32 v189, v189, v154
	v_fma_f32 v155, v216, v155, v224
	v_fma_f32 v189, v217, v189, v225
	v_cvt_pk_bf16_f32 v28, v155, v189
	ds_write_b16 v86, v28 offset:6528
	ds_write_b16_d16_hi v86, v28 offset:6800
	v_lshlrev_b32_e32 v155, 16, v29
	v_and_b32_e32 v189, 0xffff0000, v29
	v_fmac_f32_e32 v155, 0xbaaaaaab, v77
	v_fmac_f32_e32 v189, 0xbaaaaaab, v77
	v_mul_f32_e32 v155, v155, v154
	v_mul_f32_e32 v189, v189, v154
	v_fma_f32 v155, v218, v155, v226
	v_fma_f32 v189, v219, v189, v227
	v_cvt_pk_bf16_f32 v29, v155, v189
	ds_write_b16 v86, v29 offset:7072
	ds_write_b16_d16_hi v86, v29 offset:7344
	v_lshlrev_b32_e32 v155, 16, v30
	v_and_b32_e32 v189, 0xffff0000, v30
	v_fmac_f32_e32 v155, 0xbaaaaaab, v77
	v_fmac_f32_e32 v189, 0xbaaaaaab, v77
	v_mul_f32_e32 v155, v155, v154
	v_mul_f32_e32 v189, v189, v154
	v_fma_f32 v155, v220, v155, v228
	v_fma_f32 v189, v221, v189, v229
	v_cvt_pk_bf16_f32 v30, v155, v189
	ds_write_b16 v86, v30 offset:7616
	ds_write_b16_d16_hi v86, v30 offset:7888
	v_lshlrev_b32_e32 v155, 16, v31
	v_and_b32_e32 v189, 0xffff0000, v31
	v_fmac_f32_e32 v155, 0xbaaaaaab, v77
	v_fmac_f32_e32 v189, 0xbaaaaaab, v77
	v_mul_f32_e32 v155, v155, v154
	v_mul_f32_e32 v189, v189, v154
	v_fma_f32 v155, v222, v155, v230
	v_fma_f32 v189, v223, v189, v231
	v_cvt_pk_bf16_f32 v31, v155, v189
	ds_write_b16 v86, v31 offset:8160
	ds_write_b16_d16_hi v86, v31 offset:8432
	s_waitcnt lgkmcnt(0)
	s_barrier
	s_waitcnt vmcnt(20)
	ds_read_b128 v[200:203], v87 offset:0
	ds_read_b128 v[204:207], v87 offset:64
	ds_read_b128 v[208:211], v87 offset:128
	ds_read_b128 v[212:215], v87 offset:192
	ds_read_b128 v[216:219], v87 offset:1088
	ds_read_b128 v[220:223], v87 offset:1152
	ds_read_b128 v[224:227], v87 offset:1216
	ds_read_b128 v[228:231], v87 offset:1280
	s_waitcnt lgkmcnt(4)
	v_mfma_f32_16x16x32_bf16 v[78:81], v[200:203], v[32:35], 0
	v_mfma_f32_16x16x32_bf16 v[78:81], v[204:207], v[36:39], v[78:81]
	v_mfma_f32_16x16x32_bf16 v[78:81], v[208:211], v[40:43], v[78:81]
	v_mfma_f32_16x16x32_bf16 v[78:81], v[212:215], v[44:47], v[78:81]
	ds_read_b128 v[200:203], v87 offset:8704
	ds_read_b128 v[204:207], v87 offset:8768
	ds_read_b128 v[208:211], v87 offset:8832
	ds_read_b128 v[212:215], v87 offset:8896
	s_waitcnt lgkmcnt(4)
	v_mfma_f32_16x16x32_bf16 v[94:97], v[216:219], v[32:35], 0
	v_mfma_f32_16x16x32_bf16 v[94:97], v[220:223], v[36:39], v[94:97]
	v_mfma_f32_16x16x32_bf16 v[94:97], v[224:227], v[40:43], v[94:97]
	v_mfma_f32_16x16x32_bf16 v[94:97], v[228:231], v[44:47], v[94:97]
	ds_read_b128 v[216:219], v87 offset:9792
	ds_read_b128 v[220:223], v87 offset:9856
	ds_read_b128 v[224:227], v87 offset:9920
	ds_read_b128 v[228:231], v87 offset:9984
	s_waitcnt lgkmcnt(4)
	v_mfma_f32_16x16x32_bf16 v[142:145], v[200:203], v[32:35], 0
	v_mfma_f32_16x16x32_bf16 v[142:145], v[204:207], v[36:39], v[142:145]
	v_mfma_f32_16x16x32_bf16 v[142:145], v[208:211], v[40:43], v[142:145]
	v_mfma_f32_16x16x32_bf16 v[142:145], v[212:215], v[44:47], v[142:145]
	ds_read_b128 v[200:203], v87 offset:17408
	ds_read_b128 v[204:207], v87 offset:17472
	ds_read_b128 v[208:211], v87 offset:17536
	ds_read_b128 v[212:215], v87 offset:17600
	v_add_f32_e32 v78, v64, v78
	v_add_f32_e32 v79, v64, v79
	v_add_f32_e32 v80, v64, v80
	v_add_f32_e32 v81, v64, v81
	v_lshlrev_b32_e32 v155, 16, v48
	v_and_b32_e32 v189, 0xffff0000, v48
	v_mul_f32_e32 v78, v78, v155
	v_mul_f32_e32 v79, v79, v189
	v_lshlrev_b32_e32 v155, 16, v49
	v_and_b32_e32 v189, 0xffff0000, v49
	v_mul_f32_e32 v80, v80, v155
	v_mul_f32_e32 v81, v81, v189
	v_cvt_pk_bf16_f32 v48, v78, v79
	v_cvt_pk_bf16_f32 v49, v80, v81
	v_add_f32_e32 v94, v64, v94
	v_add_f32_e32 v95, v64, v95
	v_add_f32_e32 v96, v64, v96
	v_add_f32_e32 v97, v64, v97
	v_lshlrev_b32_e32 v155, 16, v50
	v_and_b32_e32 v189, 0xffff0000, v50
	v_mul_f32_e32 v94, v94, v155
	v_mul_f32_e32 v95, v95, v189
	v_lshlrev_b32_e32 v155, 16, v51
	v_and_b32_e32 v189, 0xffff0000, v51
	v_mul_f32_e32 v96, v96, v155
	v_mul_f32_e32 v97, v97, v189
	v_cvt_pk_bf16_f32 v50, v94, v95
	v_cvt_pk_bf16_f32 v51, v96, v97
	global_store_dwordx4 v93, v[48:51], s[68:69]
	s_waitcnt lgkmcnt(4)
	v_mfma_f32_16x16x32_bf16 v[146:149], v[216:219], v[32:35], 0
	v_mfma_f32_16x16x32_bf16 v[146:149], v[220:223], v[36:39], v[146:149]
	v_mfma_f32_16x16x32_bf16 v[146:149], v[224:227], v[40:43], v[146:149]
	v_mfma_f32_16x16x32_bf16 v[146:149], v[228:231], v[44:47], v[146:149]
	ds_read_b128 v[216:219], v87 offset:18496
	ds_read_b128 v[220:223], v87 offset:18560
	ds_read_b128 v[224:227], v87 offset:18624
	ds_read_b128 v[228:231], v87 offset:18688
	s_waitcnt lgkmcnt(4)
	v_mfma_f32_16x16x32_bf16 v[78:81], v[200:203], v[32:35], 0
	v_mfma_f32_16x16x32_bf16 v[78:81], v[204:207], v[36:39], v[78:81]
	v_mfma_f32_16x16x32_bf16 v[78:81], v[208:211], v[40:43], v[78:81]
	v_mfma_f32_16x16x32_bf16 v[78:81], v[212:215], v[44:47], v[78:81]
	ds_read_b128 v[200:203], v87 offset:26112
	ds_read_b128 v[204:207], v87 offset:26176
	ds_read_b128 v[208:211], v87 offset:26240
	ds_read_b128 v[212:215], v87 offset:26304
	v_add_f32_e32 v142, v64, v142
	v_add_f32_e32 v143, v64, v143
	v_add_f32_e32 v144, v64, v144
	v_add_f32_e32 v145, v64, v145
	v_lshlrev_b32_e32 v155, 16, v52
	v_and_b32_e32 v189, 0xffff0000, v52
	v_mul_f32_e32 v142, v142, v155
	v_mul_f32_e32 v143, v143, v189
	v_lshlrev_b32_e32 v155, 16, v53
	v_and_b32_e32 v189, 0xffff0000, v53
	v_mul_f32_e32 v144, v144, v155
	v_mul_f32_e32 v145, v145, v189
	v_cvt_pk_bf16_f32 v52, v142, v143
	v_cvt_pk_bf16_f32 v53, v144, v145
	v_add_f32_e32 v146, v64, v146
	v_add_f32_e32 v147, v64, v147
	v_add_f32_e32 v148, v64, v148
	v_add_f32_e32 v149, v64, v149
	v_lshlrev_b32_e32 v155, 16, v54
	v_and_b32_e32 v189, 0xffff0000, v54
	v_mul_f32_e32 v146, v146, v155
	v_mul_f32_e32 v147, v147, v189
	v_lshlrev_b32_e32 v155, 16, v55
	v_and_b32_e32 v189, 0xffff0000, v55
	v_mul_f32_e32 v148, v148, v155
	v_mul_f32_e32 v149, v149, v189
	v_cvt_pk_bf16_f32 v54, v146, v147
	v_cvt_pk_bf16_f32 v55, v148, v149
	global_store_dwordx4 v93, v[52:55], s[68:69] offset:64
	s_waitcnt lgkmcnt(4)
	v_mfma_f32_16x16x32_bf16 v[94:97], v[216:219], v[32:35], 0
	v_mfma_f32_16x16x32_bf16 v[94:97], v[220:223], v[36:39], v[94:97]
	v_mfma_f32_16x16x32_bf16 v[94:97], v[224:227], v[40:43], v[94:97]
	v_mfma_f32_16x16x32_bf16 v[94:97], v[228:231], v[44:47], v[94:97]
	ds_read_b128 v[216:219], v87 offset:27200
	ds_read_b128 v[220:223], v87 offset:27264
	ds_read_b128 v[224:227], v87 offset:27328
	ds_read_b128 v[228:231], v87 offset:27392
	s_waitcnt lgkmcnt(4)
	v_mfma_f32_16x16x32_bf16 v[142:145], v[200:203], v[32:35], 0
	v_mfma_f32_16x16x32_bf16 v[142:145], v[204:207], v[36:39], v[142:145]
	v_mfma_f32_16x16x32_bf16 v[142:145], v[208:211], v[40:43], v[142:145]
	v_mfma_f32_16x16x32_bf16 v[142:145], v[212:215], v[44:47], v[142:145]
	v_add_f32_e32 v78, v64, v78
	v_add_f32_e32 v79, v64, v79
	v_add_f32_e32 v80, v64, v80
	v_add_f32_e32 v81, v64, v81
	v_lshlrev_b32_e32 v155, 16, v56
	v_and_b32_e32 v189, 0xffff0000, v56
	v_mul_f32_e32 v78, v78, v155
	v_mul_f32_e32 v79, v79, v189
	v_lshlrev_b32_e32 v155, 16, v57
	v_and_b32_e32 v189, 0xffff0000, v57
	v_mul_f32_e32 v80, v80, v155
	v_mul_f32_e32 v81, v81, v189
	v_cvt_pk_bf16_f32 v56, v78, v79
	v_cvt_pk_bf16_f32 v57, v80, v81
	v_add_f32_e32 v94, v64, v94
	v_add_f32_e32 v95, v64, v95
	v_add_f32_e32 v96, v64, v96
	v_add_f32_e32 v97, v64, v97
	v_lshlrev_b32_e32 v155, 16, v58
	v_and_b32_e32 v189, 0xffff0000, v58
	v_mul_f32_e32 v94, v94, v155
	v_mul_f32_e32 v95, v95, v189
	v_lshlrev_b32_e32 v155, 16, v59
	v_and_b32_e32 v189, 0xffff0000, v59
	v_mul_f32_e32 v96, v96, v155
	v_mul_f32_e32 v97, v97, v189
	v_cvt_pk_bf16_f32 v58, v94, v95
	v_cvt_pk_bf16_f32 v59, v96, v97
	global_store_dwordx4 v93, v[56:59], s[68:69] offset:128
	s_waitcnt lgkmcnt(0)
	v_mfma_f32_16x16x32_bf16 v[146:149], v[216:219], v[32:35], 0
	v_mfma_f32_16x16x32_bf16 v[146:149], v[220:223], v[36:39], v[146:149]
	v_mfma_f32_16x16x32_bf16 v[146:149], v[224:227], v[40:43], v[146:149]
	v_mfma_f32_16x16x32_bf16 v[146:149], v[228:231], v[44:47], v[146:149]
	s_nop 7
	v_add_f32_e32 v142, v64, v142
	v_add_f32_e32 v143, v64, v143
	v_add_f32_e32 v144, v64, v144
	v_add_f32_e32 v145, v64, v145
	v_lshlrev_b32_e32 v155, 16, v60
	v_and_b32_e32 v189, 0xffff0000, v60
	v_mul_f32_e32 v142, v142, v155
	v_mul_f32_e32 v143, v143, v189
	v_lshlrev_b32_e32 v155, 16, v61
	v_and_b32_e32 v189, 0xffff0000, v61
	v_mul_f32_e32 v144, v144, v155
	v_mul_f32_e32 v145, v145, v189
	v_cvt_pk_bf16_f32 v60, v142, v143
	v_cvt_pk_bf16_f32 v61, v144, v145
	v_add_f32_e32 v146, v64, v146
	v_add_f32_e32 v147, v64, v147
	v_add_f32_e32 v148, v64, v148
	v_add_f32_e32 v149, v64, v149
	v_lshlrev_b32_e32 v155, 16, v62
	v_and_b32_e32 v189, 0xffff0000, v62
	v_mul_f32_e32 v146, v146, v155
	v_mul_f32_e32 v147, v147, v189
	v_lshlrev_b32_e32 v155, 16, v63
	v_and_b32_e32 v189, 0xffff0000, v63
	v_mul_f32_e32 v148, v148, v155
	v_mul_f32_e32 v149, v149, v189
	v_cvt_pk_bf16_f32 v62, v146, v147
	v_cvt_pk_bf16_f32 v63, v148, v149
	global_store_dwordx4 v93, v[60:63], s[68:69] offset:192
	s_barrier
	s_mov_b32 s16, s70
	s_cmpk_lt_u32 s16, 0x600
	s_cbranch_scc0 .Lgm_done
	s_branch .Lgm_loop
